# baseline (speedup 1.0000x reference)
; #define PG8_STAGE(bufoff, gbase, voff) do { _Pragma("unroll") for (int _i = 0; _i < 2; ++_i) \
;         __builtin_amdgcn_global_load_lds((const unsigned*)((const char*)(gbase) + (voff)[_i]), (PG8_LAS unsigned*)(lds + (bufoff) + ldsw + _i * 8192), 16, 0, 0); } while (0)
; #define PG8_LDA(dst, b, h) do { _Pragma("unroll") for (int m = 0; m < 4; ++m) _Pragma("unroll") for (int k = 0; k < 2; ++k) dst[m][k] = *(const PG8_LAS bf16x8*)(lds + PG8_SA(b, h) + aoff + m * 2048 + k * 1024); } while (0)
; #define PG8_LDB(dst, b, h) do { _Pragma("unroll") for (int n = 0; n < 2; ++n) _Pragma("unroll") for (int k = 0; k < 2; ++k) dst[n][k] = *(const PG8_LAS bf16x8*)(lds + PG8_SB(b, h) + boff + n * 2048 + k * 1024); } while (0)
; #define PG8_MMA(ai, bj, At, Bt) do { __builtin_amdgcn_s_setprio(1); _Pragma("unroll") for (int m = 0; m < 4; ++m) _Pragma("unroll") for (int n = 0; n < 2; ++n) _Pragma("unroll") for (int k = 0; k < 2; ++k) \
;         acc[ai][bj][m][n] = __builtin_amdgcn_mfma_f32_16x16x32_bf16(Bt[n][k], At[m][k], acc[ai][bj][m][n], 0, 0, 0); __builtin_amdgcn_s_setprio(0); } while (0)
; template <class Epi, class Sched, bool ALIGN_EPI = false, bool SP2 = false>
; __device__ __forceinline__ void gemm_phase(PG8_LAS unsigned char* lds, const Gemm g, const Sched& S, const Epi& E, const int tid) {
;     ...
;         const bool has_next = S.next(ui + 1, nxt);
;         const char* nA = has_next ? (const char*)g.A + (size_t)nxt.pm * tstep : cA; const char* nB = has_next ? (const char*)g.Bt + (size_t)nxt.pn * tstep : cB;
;         for (int t = 0; t < nt; t += 2) {
;             const bool last = (t == nt - 2);
;             const char* a1 = cA + (size_t)(t + 1) * kstep;
;             const char* a2 = last ? nA : cA + (size_t)(t + 2) * kstep; const char* b2 = last ? nB : cB + (size_t)(t + 2) * kstep;
;             const char* a3 = a2 + kstep; const char* b3 = b2 + kstep;
;             if (last && has_next) S.a_ready(nxt);
;             if constexpr (SP2) {
;             PG8_LDB(B0, 0, 0); PG8_LDB(B1, 0, 1); PG8_SCHED; PG8_LDA(At, 0, 0); PG8_STAGE(PG8_SA(1, 1), a1 + hstep, voffA);
;             PG8_WAIT_V(8); PG8_WAIT_L(0); PG8_BAR; PG8_MMA(0, 0, At, B0); PG8_MMA(0, 1, At, B1); PG8_BAR; PG8_SCHED;
;             PG8_LDA(At, 0, 1); PG8_STAGE(PG8_SB(0, 0), b2, voffB); PG8_STAGE(PG8_SB(0, 1), b2 + hstep, voffB); PG8_STAGE(PG8_SA(0, 0), a2, voffA);
.LBB0_59:
	s_add_u32 s26, s26, 0x80
	s_addc_u32 s27, s27, 0
	s_add_u32 s36, s30, 0x100
	s_addc_u32 s37, s31, 0
	s_mov_b32 s30, 0
	s_add_i32 s44, s30, 2
	s_add_u32 s45, s26, 0x80
	s_addc_u32 s31, s27, 0
	s_add_i32 s63, 0, 0x10000
	s_cmp_eq_u32 s58, s30
	s_cselect_b32 s31, s21, s31
	s_cselect_b32 s30, s20, s45
	s_cselect_b32 s65, s23, s37
	s_cselect_b32 s64, s22, s36
	s_add_i32 s45, 0, 0x14000
	v_add_u32_e32 v154, s63, v143
	v_add_u32_e32 v158, s45, v143
	ds_read_b128 v[138:141], v154
	ds_read_b128 v[146:149], v154 offset:1024
	ds_read_b128 v[150:153], v154 offset:2048
	ds_read_b128 v[154:157], v154 offset:3072
	ds_read_b128 v[162:165], v158
	ds_read_b128 v[166:169], v158 offset:1024
	ds_read_b128 v[170:173], v158 offset:2048
	ds_read_b128 v[184:187], v158 offset:3072
	v_lshl_add_u64 v[158:159], s[26:27], 0, v[134:135]
	s_add_i32 m0, s47, 0xc000
	ds_read_b128 v[188:191], v145
	ds_read_b128 v[192:195], v145 offset:1024
	ds_read_b128 v[208:211], v145 offset:2048
	ds_read_b128 v[214:217], v145 offset:3072
	ds_read_b128 v[218:221], v145 offset:4096
	ds_read_b128 v[222:225], v145 offset:5120
	ds_read_b128 v[226:229], v145 offset:6144
	ds_read_b128 v[230:233], v145 offset:7168
	global_load_lds_dwordx4 v[158:159], off
	v_lshl_add_u64 v[158:159], s[26:27], 0, v[136:137]
	s_add_i32 m0, s47, 0xe000
	s_nop 0
	global_load_lds_dwordx4 v[158:159], off
	s_waitcnt vmcnt(8)
	s_waitcnt lgkmcnt(0)
	s_barrier
	s_setprio 1
	s_waitcnt lgkmcnt(0)
	v_mfma_f32_16x16x32_bf16 v[124:127], v[138:141], v[188:191], 0
	v_mfma_f32_16x16x32_bf16 v[120:123], v[150:153], v[188:191], 0
	v_mfma_f32_16x16x32_bf16 v[108:111], v[138:141], v[208:211], 0
	v_mfma_f32_16x16x32_bf16 v[104:107], v[150:153], v[208:211], 0
	v_mfma_f32_16x16x32_bf16 v[92:95], v[138:141], v[218:221], 0
	v_mfma_f32_16x16x32_bf16 v[88:91], v[150:153], v[218:221], 0
	v_mfma_f32_16x16x32_bf16 v[76:79], v[138:141], v[226:229], 0
	v_mfma_f32_16x16x32_bf16 v[72:75], v[150:153], v[226:229], 0
	v_mfma_f32_16x16x32_bf16 v[124:127], v[146:149], v[192:195], v[124:127]
	v_mfma_f32_16x16x32_bf16 v[120:123], v[154:157], v[192:195], v[120:123]
	v_mfma_f32_16x16x32_bf16 v[108:111], v[146:149], v[214:217], v[108:111]
	v_mfma_f32_16x16x32_bf16 v[104:107], v[154:157], v[214:217], v[104:107]
	v_mfma_f32_16x16x32_bf16 v[92:95], v[146:149], v[222:225], v[92:95]
	v_mfma_f32_16x16x32_bf16 v[88:91], v[154:157], v[222:225], v[88:91]
	v_mfma_f32_16x16x32_bf16 v[76:79], v[146:149], v[230:233], v[76:79]
	v_mfma_f32_16x16x32_bf16 v[72:75], v[154:157], v[230:233], v[72:75]
	s_setprio 0
	s_setprio 1
	v_mfma_f32_16x16x32_bf16 v[116:119], v[162:165], v[188:191], 0
	v_mfma_f32_16x16x32_bf16 v[112:115], v[170:173], v[188:191], 0
	v_mfma_f32_16x16x32_bf16 v[100:103], v[162:165], v[208:211], 0
	v_mfma_f32_16x16x32_bf16 v[96:99], v[170:173], v[208:211], 0
	v_mfma_f32_16x16x32_bf16 v[84:87], v[162:165], v[218:221], 0
	v_mfma_f32_16x16x32_bf16 v[80:83], v[170:173], v[218:221], 0
	v_mfma_f32_16x16x32_bf16 v[68:71], v[162:165], v[226:229], 0
	v_mfma_f32_16x16x32_bf16 v[64:67], v[170:173], v[226:229], 0
	v_mfma_f32_16x16x32_bf16 v[116:119], v[166:169], v[192:195], v[116:119]
	v_mfma_f32_16x16x32_bf16 v[112:115], v[184:187], v[192:195], v[112:115]
	v_mfma_f32_16x16x32_bf16 v[100:103], v[166:169], v[214:217], v[100:103]
	v_mfma_f32_16x16x32_bf16 v[96:99], v[184:187], v[214:217], v[96:99]
	v_mfma_f32_16x16x32_bf16 v[84:87], v[166:169], v[222:225], v[84:87]
	v_mfma_f32_16x16x32_bf16 v[80:83], v[184:187], v[222:225], v[80:83]
	v_mfma_f32_16x16x32_bf16 v[68:71], v[166:169], v[230:233], v[68:71]
	v_mfma_f32_16x16x32_bf16 v[64:67], v[184:187], v[230:233], v[64:67]
	s_setprio 0
	s_barrier
	s_add_i32 s63, s63, s46
	v_lshl_add_u64 v[158:159], s[64:65], 0, v[160:161]
	s_mov_b32 m0, s63
	ds_read_b128 v[188:191], v145 offset:16384
	ds_read_b128 v[192:195], v145 offset:17408
	ds_read_b128 v[208:211], v145 offset:18432
	ds_read_b128 v[214:217], v145 offset:19456
	ds_read_b128 v[218:221], v145 offset:20480
	ds_read_b128 v[222:225], v145 offset:21504
	ds_read_b128 v[226:229], v145 offset:22528
	ds_read_b128 v[230:233], v145 offset:23552
	global_load_lds_dwordx4 v[158:159], off
	s_add_i32 m0, s63, 0x2000
	v_lshl_add_u64 v[174:175], s[64:65], 0, v[132:133]
	s_add_u32 s64, s64, s12
	s_addc_u32 s65, s65, 0
	s_add_i32 s45, s45, s46
	global_load_lds_dwordx4 v[174:175], off
	v_lshl_add_u64 v[178:179], s[64:65], 0, v[160:161]
	s_mov_b32 m0, s45
	v_lshl_add_u64 v[180:181], s[64:65], 0, v[132:133]
	global_load_lds_dwordx4 v[178:179], off
	s_add_i32 m0, s45, 0x2000
	v_lshl_add_u64 v[196:197], s[30:31], 0, v[128:129]
	global_load_lds_dwordx4 v[180:181], off
	s_mov_b32 m0, s47
	v_lshl_add_u64 v[198:199], s[30:31], 0, v[130:131]
	global_load_lds_dwordx4 v[196:197], off
	s_mov_b32 m0, s48
	s_nop 0
	global_load_lds_dwordx4 v[198:199], off
	s_cmp_lt_u32 s59, 2
	s_cbranch_scc1 .Lmy_w8_0
	s_waitcnt vmcnt(8)
	s_branch .Lmy_wj_0

; #define PG8_STAGE(bufoff, gbase, voff) do { _Pragma("unroll") for (int _i = 0; _i < 2; ++_i) \
;         __builtin_amdgcn_global_load_lds((const unsigned*)((const char*)(gbase) + (voff)[_i]), (PG8_LAS unsigned*)(lds + (bufoff) + ldsw + _i * 8192), 16, 0, 0); } while (0)
; #define PG8_LDA(dst, b, h) do { _Pragma("unroll") for (int m = 0; m < 4; ++m) _Pragma("unroll") for (int k = 0; k < 2; ++k) dst[m][k] = *(const PG8_LAS bf16x8*)(lds + PG8_SA(b, h) + aoff + m * 2048 + k * 1024); } while (0)
; #define PG8_LDB(dst, b, h) do { _Pragma("unroll") for (int n = 0; n < 2; ++n) _Pragma("unroll") for (int k = 0; k < 2; ++k) dst[n][k] = *(const PG8_LAS bf16x8*)(lds + PG8_SB(b, h) + boff + n * 2048 + k * 1024); } while (0)
; #define PG8_MMA(ai, bj, At, Bt) do { __builtin_amdgcn_s_setprio(1); _Pragma("unroll") for (int m = 0; m < 4; ++m) _Pragma("unroll") for (int n = 0; n < 2; ++n) _Pragma("unroll") for (int k = 0; k < 2; ++k) \
;         acc[ai][bj][m][n] = __builtin_amdgcn_mfma_f32_16x16x32_bf16(Bt[n][k], At[m][k], acc[ai][bj][m][n], 0, 0, 0); __builtin_amdgcn_s_setprio(0); } while (0)
; template <class Epi, class Sched, bool ALIGN_EPI = false, bool SP2 = false>
; __device__ __forceinline__ void gemm_phase(PG8_LAS unsigned char* lds, const Gemm g, const Sched& S, const Epi& E, const int tid) {
;     ...
;         const bool has_next = S.next(ui + 1, nxt);
;         const char* nA = has_next ? (const char*)g.A + (size_t)nxt.pm * tstep : cA; const char* nB = has_next ? (const char*)g.Bt + (size_t)nxt.pn * tstep : cB;
;         for (int t = 0; t < nt; t += 2) {
;             const bool last = (t == nt - 2);
;             const char* a1 = cA + (size_t)(t + 1) * kstep;
;             const char* a2 = last ? nA : cA + (size_t)(t + 2) * kstep; const char* b2 = last ? nB : cB + (size_t)(t + 2) * kstep;
;             const char* a3 = a2 + kstep; const char* b3 = b2 + kstep;
;             if (last && has_next) S.a_ready(nxt);
;             if constexpr (SP2) {
;             PG8_LDB(B0, 0, 0); PG8_LDB(B1, 0, 1); PG8_SCHED; PG8_LDA(At, 0, 0); PG8_STAGE(PG8_SA(1, 1), a1 + hstep, voffA);
;             PG8_WAIT_V(8); PG8_WAIT_L(0); PG8_BAR; PG8_MMA(0, 0, At, B0); PG8_MMA(0, 1, At, B1); PG8_BAR; PG8_SCHED;
;             PG8_LDA(At, 0, 1); PG8_STAGE(PG8_SB(0, 0), b2, voffB); PG8_STAGE(PG8_SB(0, 1), b2 + hstep, voffB); PG8_STAGE(PG8_SA(0, 0), a2, voffA);
.LBB0_466:
	s_ashr_i32 s51, s50, 31
	s_lshl_b64 s[20:21], s[50:51], 19
	s_add_u32 s52, s12, s20
	s_addc_u32 s53, s13, s21
	s_and_b64 s[20:21], s[40:41], exec
	s_cselect_b32 s1, s53, s15
	s_cselect_b32 s36, s52, s14
	s_ashr_i32 s49, s48, 31
	s_lshl_b64 s[20:21], s[48:49], 19
	s_add_u32 s68, s22, s20
	s_addc_u32 s69, s23, s21
	s_and_b64 s[20:21], s[40:41], exec
	s_cselect_b32 s37, s69, s17
	s_cselect_b32 s42, s68, s16
	s_add_u32 s14, s14, 0x40080
	s_addc_u32 s15, s15, 0
	s_add_u32 s43, s16, 0x100
	s_addc_u32 s49, s17, 0
	s_mov_b32 s51, -2
	s_add_u32 s16, s14, 0xfffc0080
	s_addc_u32 s17, s15, -1
	s_add_i32 s56, 0, 0x10000
	s_cmp_eq_u32 s51, 12
	s_cselect_b32 s21, s1, s17
	s_cselect_b32 s20, s36, s16
	v_add_u32_e32 v138, s56, v147
	s_cselect_b32 s17, s37, s49
	s_cselect_b32 s16, s42, s43
	s_add_i32 s58, 0, 0x14000
	ds_read_b128 v[140:143], v138
	ds_read_b128 v[154:157], v138 offset:1024
	ds_read_b128 v[162:165], v138 offset:2048
	ds_read_b128 v[166:169], v138 offset:3072
	v_add_u32_e32 v138, s58, v147
	ds_read_b128 v[170:173], v138
	ds_read_b128 v[184:187], v138 offset:1024
	ds_read_b128 v[188:191], v138 offset:2048
	ds_read_b128 v[192:195], v138 offset:3072
	v_lshl_add_u64 v[158:159], s[14:15], 0, v[134:135]
	s_add_i32 m0, s3, 0xc000
	ds_read_b128 v[208:211], v153
	ds_read_b128 v[214:217], v153 offset:1024
	ds_read_b128 v[218:221], v153 offset:2048
	ds_read_b128 v[222:225], v153 offset:3072
	ds_read_b128 v[226:229], v153 offset:4096
	ds_read_b128 v[230:233], v153 offset:5120
	ds_read_b128 v[234:237], v153 offset:6144
	ds_read_b128 v[238:241], v153 offset:7168
	global_load_lds_dwordx4 v[158:159], off
	v_lshl_add_u64 v[158:159], s[14:15], 0, v[136:137]
	s_add_i32 m0, s3, 0xe000
	s_nop 0
	global_load_lds_dwordx4 v[158:159], off
	s_waitcnt vmcnt(8)
	s_waitcnt lgkmcnt(0)
	s_barrier
	s_setprio 1
	s_waitcnt lgkmcnt(0)
	v_mfma_f32_16x16x32_bf16 v[124:127], v[140:143], v[208:211], 0
	v_mfma_f32_16x16x32_bf16 v[120:123], v[162:165], v[208:211], 0
	v_mfma_f32_16x16x32_bf16 v[108:111], v[140:143], v[218:221], 0
	v_mfma_f32_16x16x32_bf16 v[104:107], v[162:165], v[218:221], 0
	v_mfma_f32_16x16x32_bf16 v[92:95], v[140:143], v[226:229], 0
	v_mfma_f32_16x16x32_bf16 v[88:91], v[162:165], v[226:229], 0
	v_mfma_f32_16x16x32_bf16 v[76:79], v[140:143], v[234:237], 0
	v_mfma_f32_16x16x32_bf16 v[72:75], v[162:165], v[234:237], 0
	v_mfma_f32_16x16x32_bf16 v[124:127], v[154:157], v[214:217], v[124:127]
	v_mfma_f32_16x16x32_bf16 v[120:123], v[166:169], v[214:217], v[120:123]
	v_mfma_f32_16x16x32_bf16 v[108:111], v[154:157], v[222:225], v[108:111]
	v_mfma_f32_16x16x32_bf16 v[104:107], v[166:169], v[222:225], v[104:107]
	v_mfma_f32_16x16x32_bf16 v[92:95], v[154:157], v[230:233], v[92:95]
	v_mfma_f32_16x16x32_bf16 v[88:91], v[166:169], v[230:233], v[88:91]
	v_mfma_f32_16x16x32_bf16 v[76:79], v[154:157], v[238:241], v[76:79]
	v_mfma_f32_16x16x32_bf16 v[72:75], v[166:169], v[238:241], v[72:75]
	s_setprio 0
	s_setprio 1
	v_mfma_f32_16x16x32_bf16 v[116:119], v[170:173], v[208:211], 0
	v_mfma_f32_16x16x32_bf16 v[112:115], v[188:191], v[208:211], 0
	v_mfma_f32_16x16x32_bf16 v[100:103], v[170:173], v[218:221], 0
	v_mfma_f32_16x16x32_bf16 v[96:99], v[188:191], v[218:221], 0
	v_mfma_f32_16x16x32_bf16 v[84:87], v[170:173], v[226:229], 0
	v_mfma_f32_16x16x32_bf16 v[80:83], v[188:191], v[226:229], 0
	v_mfma_f32_16x16x32_bf16 v[68:71], v[170:173], v[234:237], 0
	v_mfma_f32_16x16x32_bf16 v[64:67], v[188:191], v[234:237], 0
	v_mfma_f32_16x16x32_bf16 v[116:119], v[184:187], v[214:217], v[116:119]
	v_mfma_f32_16x16x32_bf16 v[112:115], v[192:195], v[214:217], v[112:115]
	v_mfma_f32_16x16x32_bf16 v[100:103], v[184:187], v[222:225], v[100:103]
	v_mfma_f32_16x16x32_bf16 v[96:99], v[192:195], v[222:225], v[96:99]
	v_mfma_f32_16x16x32_bf16 v[84:87], v[184:187], v[230:233], v[84:87]
	v_mfma_f32_16x16x32_bf16 v[80:83], v[192:195], v[230:233], v[80:83]
	v_mfma_f32_16x16x32_bf16 v[68:71], v[184:187], v[238:241], v[68:71]
	v_mfma_f32_16x16x32_bf16 v[64:67], v[192:195], v[238:241], v[64:67]
	s_setprio 0
	s_barrier
	s_add_i32 s56, s56, s27
	v_lshl_add_u64 v[158:159], s[16:17], 0, v[160:161]
	s_mov_b32 m0, s56
	ds_read_b128 v[208:211], v153 offset:16384
	ds_read_b128 v[214:217], v153 offset:17408
	ds_read_b128 v[218:221], v153 offset:18432
	ds_read_b128 v[222:225], v153 offset:19456
	ds_read_b128 v[226:229], v153 offset:20480
	ds_read_b128 v[230:233], v153 offset:21504
	ds_read_b128 v[234:237], v153 offset:22528
	ds_read_b128 v[238:241], v153 offset:23552
	global_load_lds_dwordx4 v[158:159], off
	s_add_i32 m0, s56, 0x2000
	s_add_u32 s56, s16, 0x40000
	v_lshl_add_u64 v[174:175], s[16:17], 0, v[132:133]
	s_addc_u32 s57, s17, 0
	s_add_i32 s58, s58, s27
	global_load_lds_dwordx4 v[174:175], off
	v_lshl_add_u64 v[178:179], s[56:57], 0, v[160:161]
	s_mov_b32 m0, s58
	v_lshl_add_u64 v[180:181], s[20:21], 0, v[130:131]
	global_load_lds_dwordx4 v[178:179], off
	v_lshl_add_u64 v[178:179], s[56:57], 0, v[132:133]
	s_add_i32 m0, s58, 0x2000
	s_nop 0
	global_load_lds_dwordx4 v[178:179], off
	v_lshl_add_u64 v[178:179], s[20:21], 0, v[128:129]
	s_mov_b32 m0, s3
	s_nop 0
	global_load_lds_dwordx4 v[178:179], off
	s_mov_b32 m0, s30
	s_nop 0
	global_load_lds_dwordx4 v[180:181], off
	s_cmp_lt_u32 s83, 2
	s_cbranch_scc1 .Lmy_w8_1
	s_waitcnt vmcnt(8)
	s_branch .Lmy_wj_1
